# same stack, static s_setprio 1 on waves 0-3 (instead of 4-7) during GEMM phases, no per-phase flips
# baseline (speedup 1.0000x reference)
; #define PG8_STAGE(bufoff, gbase, voff) do { _Pragma("unroll") for (int _i = 0; _i < 2; ++_i) \
;         __builtin_amdgcn_global_load_lds((const unsigned*)((const char*)(gbase) + (voff)[_i]), (LAS unsigned*)(lds + (bufoff) + ldsw + _i * 8192), 16, 0, 0); } while (0)
; #define PG8_BAR __builtin_amdgcn_s_barrier()
; template <class Epi, bool ALIGN_EPI, class Hook = NoHook>
; __device__ __forceinline__ void gemm_phase(LAS unsigned char* lds, const Gemm g, const StaticOrder& S, const Epi& E, const Hook& HK = Hook()) {
;     int tid = threadIdx.x; asm volatile("" : "+v"(tid));
;     const int wid = __builtin_amdgcn_readfirstlane(tid >> 6), lane = tid & 63, wr = wid >> 2, wc = wid & 3, fr = lane & 15, fq = lane >> 4;
;     const int K = g.K, nt = K / BK;
;     unsigned voffA[2], voffB[2];
; #pragma unroll
;     for (int i = 0; i < 2; ++i) { int R, C; stage_rc(tid * 16 + i * 8192, R, C); const int Rb = Epi::PERM ? ((R & ~31) + perm32(R & 31)) : R;
;         voffA[i] = (unsigned)(R * g.lda + C) * 2u; voffB[i] = (unsigned)(Rb * g.ldb + C) * 2u; }
;     const size_t kstep = (size_t)(BK * 2);
;     const size_t hstepA = (size_t)HALF * g.lda * 2, hstepB = (size_t)HALF * g.ldb * 2;
;     const size_t tstepA = 2 * hstepA, tstepB = 2 * hstepB;
;     const unsigned ldsw = (unsigned)wid * 1024u;
;     const int aoff = lds_byte(wr * 64 + fr, fq * 8), boff = lds_byte(wc * 32 + fr, fq * 8);
;     ...
;     Unit cur, nxt; int ui = 0;
;     if (!S.next(0, cur)) return;
;     f32x4 acc[2][2][4][2];
; #pragma unroll
;     for (int a = 0; a < 2; ++a)
; #pragma unroll
;         for (int b = 0; b < 2; ++b)
; #pragma unroll
;             for (int m = 0; m < 4; ++m)
; #pragma unroll
;                 for (int n = 0; n < 2; ++n) acc[a][b][m][n] = (f32x4){0.f, 0.f, 0.f, 0.f};
;     bf16x8 At[4][2], B0[2][2], B1[2][2];
;     const char* cA = (const char*)g.A + (size_t)cur.pm * tstepA; const char* cB = (const char*)g.Bt + (size_t)cur.pn * tstepB;
;     PG8_STAGE(PG8_SB(0, 0), cB, voffB); PG8_STAGE(PG8_SB(0, 1), cB + hstepB, voffB); PG8_STAGE(PG8_SA(0, 0), cA, voffA); PG8_STAGE(PG8_SA(0, 1), cA + hstepA, voffA);
;     if (wr == 1) PG8_BAR;
.LBB0_39:
	s_or_b64 exec, exec, s[0:1]
	s_add_u32 s48, s62, 0x7c00000
	s_addc_u32 s49, s63, 0
	s_add_u32 s46, s62, 0xbc00000
	s_addc_u32 s47, s63, 0
	s_cmpk_lt_i32 s2, 0xb00
	s_cselect_b64 s[0:1], -1, 0
	v_writelane_b32 v254, s0, 16
	v_mov_b32_e32 v9, v136
	s_barrier
	v_writelane_b32 v254, s1, 17
	s_cmpk_gt_i32 s2, 0xaff
	v_readfirstlane_b32 s1, v9
	v_writelane_b32 v254, s56, 18
	s_nop 1
	v_writelane_b32 v254, s57, 19
	s_cbranch_scc1 .LBB0_55
	v_lshlrev_b32_e32 v0, 4, v9
	v_add_u32_e32 v1, 0x2000, v0
	v_ashrrev_i32_e32 v2, 31, v1
	v_lshrrev_b32_e32 v2, 22, v2
	v_add_u32_e32 v2, v1, v2
	v_ashrrev_i32_e32 v8, 10, v2
	v_mul_i32_i24_e32 v2, 0x400, v8
	v_sub_u32_e32 v1, v1, v2
	v_lshrrev_b32_e32 v2, 4, v1
	v_bitop3_b32 v1, v2, v1, 32 bitop3:0x6c
	v_ashrrev_i32_e32 v2, 31, v1
	v_lshrrev_b32_e32 v2, 26, v2
	v_add_u32_e32 v2, v1, v2
	v_lshlrev_b32_e32 v3, 3, v8
	v_ashrrev_i32_e32 v10, 6, v2
	v_and_b32_e32 v3, -16, v3
	v_add_u32_e32 v3, v10, v3
	v_and_b32_e32 v4, 3, v10
	s_mov_b32 s0, 0xfffe0
	v_lshrrev_b32_e32 v5, 2, v3
	v_lshlrev_b32_e32 v6, 1, v3
	v_and_b32_e32 v2, 0xc0, v2
	v_and_or_b32 v4, v3, s0, v4
	v_and_b32_e32 v5, 4, v5
	v_and_b32_e32 v6, 24, v6
	v_sub_u32_e32 v1, v1, v2
	v_mov_b32_e32 v2, 1
	v_or3_b32 v4, v4, v5, v6
	v_lshlrev_b32_e32 v5, 5, v8
	v_ashrrev_i16_sdwa v1, v2, sext(v1) dst_sel:DWORD dst_unused:UNUSED_PAD src0_sel:DWORD src1_sel:BYTE_0
	v_and_b32_e32 v5, 32, v5
	v_bfe_i32 v11, v1, 0, 16
	v_add_lshl_u32 v1, v5, v11, 1
	v_lshl_add_u32 v128, v4, 12, v1
	v_lshl_add_u32 v130, v3, 12, v1
	v_bfe_i32 v1, v9, 27, 1
	v_lshrrev_b32_e32 v1, 22, v1
	v_add_u32_e32 v1, v0, v1
	v_and_b32_e32 v1, 0xfffffc00, v1
	v_sub_u32_e32 v0, v0, v1
	v_lshrrev_b32_e32 v1, 4, v0
	v_ashrrev_i32_e32 v3, 31, v9
	v_bitop3_b32 v0, v1, v0, 32 bitop3:0x6c
	v_lshrrev_b32_e32 v3, 26, v3
	v_ashrrev_i32_e32 v1, 31, v0
	v_add_u32_e32 v3, v9, v3
	v_lshrrev_b32_e32 v1, 26, v1
	v_ashrrev_i32_e32 v13, 6, v3
	v_add_u32_e32 v1, v0, v1
	v_lshlrev_b32_e32 v3, 3, v13
	v_ashrrev_i32_e32 v12, 6, v1
	v_and_b32_e32 v3, -16, v3
	v_add_u32_e32 v3, v12, v3
	v_and_b32_e32 v4, 3, v12
	s_ashr_i32 s50, s2, 31
	v_and_or_b32 v4, v3, s0, v4
	s_lshr_b32 s0, s50, 29
	s_add_i32 s0, s2, s0
	s_ashr_i32 s6, s1, 6
	s_ashr_i32 s4, s0, 3
	s_and_b32 s0, s0, -8
	s_ashr_i32 s7, s1, 8
	s_lshl_b32 s17, s6, 10
	s_sub_i32 s0, s2, s0
	s_cmp_lt_i32 s0, 0
	s_movk_i32 s51, 0x161
	s_cselect_b32 s5, s51, 0x160
	s_mul_i32 s0, s0, s5
	s_add_i32 s0, s0, s4
	s_mul_hi_i32 s4, s0, 0x2e8ba2e9
	s_lshr_b32 s5, s4, 31
	s_ashr_i32 s4, s4, 6
	s_add_i32 s4, s4, s5
	s_lshl_b32 s5, s4, 3
	s_mulk_i32 s4, 0x160
	s_sub_i32 s4, s0, s4
	s_sext_i32_i16 s0, s4
	s_bfe_u32 s0, s0, 0x3001c
	s_add_i32 s12, s4, s0
	s_sext_i32_i16 s0, s12
	s_and_b32 s12, s12, 0xfff8
	s_sub_i32 s4, s4, s12
	s_sext_i32_i16 s4, s4
	v_lshrrev_b32_e32 v5, 2, v3
	v_lshlrev_b32_e32 v6, 1, v3
	v_and_b32_e32 v1, 0xc0, v1
	s_lshr_b32 s0, s0, 3
	s_add_i32 s82, s5, s4
	v_and_b32_e32 v5, 4, v5
	v_and_b32_e32 v6, 24, v6
	v_sub_u32_e32 v0, v0, v1
	s_ashr_i32 s83, s82, 31
	s_bfe_i64 s[12:13], s[0:1], 0x100000
	v_or3_b32 v4, v4, v5, v6
	v_lshlrev_b32_e32 v5, 5, v13
	v_ashrrev_i16_sdwa v0, v2, sext(v0) dst_sel:DWORD dst_unused:UNUSED_PAD src0_sel:DWORD src1_sel:BYTE_0
	s_lshl_b64 s[4:5], s[82:83], 20
	s_lshl_b64 s[12:13], s[12:13], 20
	v_and_b32_e32 v5, 32, v5
	v_bfe_i32 v14, v0, 0, 16
	s_add_u32 s86, s66, s12
	v_add_lshl_u32 v0, v5, v14, 1
	s_addc_u32 s87, s67, s13
	s_add_i32 s71, s17, 0
	v_lshl_add_u32 v132, v4, 12, v0
	s_add_i32 m0, s71, 0x10000
	v_lshl_add_u32 v134, v3, 12, v0
	global_load_lds_dwordx4 v132, s[86:87]
	s_add_i32 m0, s71, 0x12000
	s_add_u32 s12, s86, 0x80000
	global_load_lds_dwordx4 v128, s[86:87]
	s_addc_u32 s13, s87, 0
	s_add_i32 m0, s71, 0x14000
	v_mov_b32_e32 v133, 0
	global_load_lds_dwordx4 v132, s[12:13]
	s_add_i32 m0, s71, 0x16000
	s_add_u32 s84, s48, s4
	s_addc_u32 s85, s49, s5
	s_add_i32 s72, s71, 0x2000
	global_load_lds_dwordx4 v128, s[12:13]
	s_mov_b32 m0, s71
	s_add_u32 s4, s84, 0x80000
	global_load_lds_dwordx4 v134, s[84:85]
	s_mov_b32 m0, s72
	s_addc_u32 s5, s85, 0
	s_add_i32 s73, s71, 0x4000
	global_load_lds_dwordx4 v130, s[84:85]
	s_mov_b32 m0, s73
	s_add_i32 s83, s71, 0x6000
	global_load_lds_dwordx4 v134, s[4:5]
	s_mov_b32 m0, s83
	v_mov_b32_e32 v129, v133
	global_load_lds_dwordx4 v130, s[4:5]
	v_mov_b32_e32 v135, v133
	v_mov_b32_e32 v131, v133
	s_cmp_eq_u32 s7, 1
	s_mov_b32 s90, 0
	v_lshl_add_u64 v[6:7], s[86:87], 0, v[132:133]
	v_lshl_add_u64 v[4:5], s[86:87], 0, v[128:129]
	v_lshl_add_u64 v[0:1], s[84:85], 0, v[134:135]
	s_cselect_b64 s[4:5], -1, 0
	s_cmp_lg_u32 s7, 1
	v_lshl_add_u64 v[2:3], s[84:85], 0, v[130:131]
	s_setprio 1
	s_cbranch_scc1 .LBB0_42
	s_barrier
	s_setprio 0

; #define PG8_STAGE(bufoff, gbase, voff) do { _Pragma("unroll") for (int _i = 0; _i < 2; ++_i) \
;         __builtin_amdgcn_global_load_lds((const unsigned*)((const char*)(gbase) + (voff)[_i]), (LAS unsigned*)(lds + (bufoff) + ldsw + _i * 8192), 16, 0, 0); } while (0)
; #define PG8_BAR __builtin_amdgcn_s_barrier()
; template <class Epi, bool ALIGN_EPI, class Hook = NoHook>
; __device__ __forceinline__ void gemm_phase(LAS unsigned char* lds, const Gemm g, const StaticOrder& S, const Epi& E, const Hook& HK = Hook()) {
;     int tid = threadIdx.x; asm volatile("" : "+v"(tid));
;     const int wid = __builtin_amdgcn_readfirstlane(tid >> 6), lane = tid & 63, wr = wid >> 2, wc = wid & 3, fr = lane & 15, fq = lane >> 4;
;     const int K = g.K, nt = K / BK;
;     unsigned voffA[2], voffB[2];
; #pragma unroll
;     for (int i = 0; i < 2; ++i) { int R, C; stage_rc(tid * 16 + i * 8192, R, C); const int Rb = Epi::PERM ? ((R & ~31) + perm32(R & 31)) : R;
;         voffA[i] = (unsigned)(R * g.lda + C) * 2u; voffB[i] = (unsigned)(Rb * g.ldb + C) * 2u; }
;     const size_t kstep = (size_t)(BK * 2);
;     const size_t hstepA = (size_t)HALF * g.lda * 2, hstepB = (size_t)HALF * g.ldb * 2;
;     const size_t tstepA = 2 * hstepA, tstepB = 2 * hstepB;
;     const unsigned ldsw = (unsigned)wid * 1024u;
;     const int aoff = lds_byte(wr * 64 + fr, fq * 8), boff = lds_byte(wc * 32 + fr, fq * 8);
;     ...
;     Unit cur, nxt; int ui = 0;
;     if (!S.next(0, cur)) return;
;     f32x4 acc[2][2][4][2];
; #pragma unroll
;     for (int a = 0; a < 2; ++a)
; #pragma unroll
;         for (int b = 0; b < 2; ++b)
; #pragma unroll
;             for (int m = 0; m < 4; ++m)
; #pragma unroll
;                 for (int n = 0; n < 2; ++n) acc[a][b][m][n] = (f32x4){0.f, 0.f, 0.f, 0.f};
;     bf16x8 At[4][2], B0[2][2], B1[2][2];
;     const char* cA = (const char*)g.A + (size_t)cur.pm * tstepA; const char* cB = (const char*)g.Bt + (size_t)cur.pn * tstepB;
;     PG8_STAGE(PG8_SB(0, 0), cB, voffB); PG8_STAGE(PG8_SB(0, 1), cB + hstepB, voffB); PG8_STAGE(PG8_SA(0, 0), cA, voffA); PG8_STAGE(PG8_SA(0, 1), cA + hstepA, voffA);
;     if (wr == 1) PG8_BAR;
.LBB0_112:
	v_ashrrev_i32_e32 v1, 31, v8
	v_lshrrev_b32_e32 v1, 26, v1
	v_add_u32_e32 v1, v8, v1
	v_ashrrev_i32_e32 v9, 6, v1
	v_bfe_i32 v1, v8, 27, 1
	v_lshlrev_b32_e32 v0, 4, v8
	v_lshrrev_b32_e32 v1, 22, v1
	v_add_u32_e32 v1, v0, v1
	v_and_b32_e32 v1, 0xfffffc00, v1
	v_sub_u32_e32 v1, v0, v1
	v_lshrrev_b32_e32 v2, 4, v1
	v_bitop3_b32 v1, v2, v1, 32 bitop3:0x6c
	v_ashrrev_i32_e32 v3, 31, v1
	v_lshrrev_b32_e32 v3, 26, v3
	v_lshlrev_b32_e32 v2, 3, v9
	v_add_u32_e32 v3, v1, v3
	v_and_b32_e32 v2, -16, v2
	v_ashrrev_i32_e32 v10, 6, v3
	v_and_b32_e32 v3, 0xc0, v3
	v_add_u32_e32 v2, v10, v2
	v_lshlrev_b32_e32 v4, 5, v9
	v_sub_u32_e32 v1, v1, v3
	v_mov_b32_e32 v3, 1
	s_ashr_i32 s7, s6, 3
	v_and_b32_e32 v11, 32, v4
	v_ashrrev_i16_sdwa v1, v3, sext(v1) dst_sel:DWORD dst_unused:UNUSED_PAD src0_sel:DWORD src1_sel:BYTE_0
	v_lshlrev_b32_e32 v4, 1, v2
	v_lshrrev_b32_e32 v5, 2, v2
	v_and_b32_e32 v6, 3, v10
	s_mov_b32 s6, 0x7fffe0
	v_bfe_i32 v12, v1, 0, 16
	v_and_b32_e32 v4, 24, v4
	v_and_b32_e32 v5, 4, v5
	v_and_or_b32 v6, v2, s6, v6
	s_movk_i32 s1, 0x1600
	v_add_u32_e32 v1, v11, v12
	v_or3_b32 v4, v6, v5, v4
	v_mul_lo_u32 v2, v2, s1
	v_add_lshl_u32 v144, v1, v2, 1
	v_mul_u32_u24_e32 v2, 0x1600, v4
	v_add_u32_e32 v0, 0x2000, v0
	v_add_lshl_u32 v146, v2, v1, 1
	v_ashrrev_i32_e32 v1, 31, v0
	v_lshrrev_b32_e32 v1, 22, v1
	s_add_i32 s5, s5, s7
	v_add_u32_e32 v1, v0, v1
	s_ashr_i32 s7, s5, 31
	v_ashrrev_i32_e32 v13, 10, v1
	s_lshr_b32 s7, s7, 27
	v_mul_i32_i24_e32 v1, 0x400, v13
	s_add_i32 s7, s5, s7
	v_sub_u32_e32 v0, v0, v1
	s_ashr_i32 s12, s7, 5
	s_andn2_b32 s7, s7, 31
	v_lshrrev_b32_e32 v1, 4, v0
	s_sub_i32 s7, s5, s7
	v_bitop3_b32 v0, v1, v0, 32 bitop3:0x6c
	s_bfe_i32 s5, s7, 0x80000
	v_ashrrev_i32_e32 v2, 31, v0
	s_bfe_u32 s5, s5, 0x2000d
	v_lshrrev_b32_e32 v2, 26, v2
	s_add_i32 s13, s7, s5
	v_lshlrev_b32_e32 v1, 3, v13
	v_add_u32_e32 v2, v0, v2
	s_bfe_i32 s5, s13, 0x80000
	s_and_b32 s13, s13, 0xfc
	v_and_b32_e32 v1, -16, v1
	v_ashrrev_i32_e32 v14, 6, v2
	v_lshlrev_b32_e32 v4, 5, v13
	s_sub_i32 s7, s7, s13
	v_add_u32_e32 v1, v14, v1
	v_and_b32_e32 v15, 32, v4
	v_and_b32_e32 v4, 3, v14
	s_lshl_b32 s12, s12, 2
	s_sext_i32_i16 s14, s5
	s_sext_i32_i8 s7, s7
	v_and_b32_e32 v2, 0xc0, v2
	v_and_or_b32 v4, v1, s6, v4
	s_ashr_i32 s6, s4, 6
	s_add_i32 s92, s12, s7
	s_ashr_i32 s12, s14, 2
	s_ashr_i32 s0, s4, 8
	v_sub_u32_e32 v0, v0, v2
	s_lshl_b32 s27, s6, 10
	s_lshr_b32 s5, s14, 2
	s_mul_hi_i32 s13, s12, 0x2c0000
	s_mul_i32 s12, s12, 0x2c0000
	v_ashrrev_i16_sdwa v0, v3, sext(v0) dst_sel:DWORD dst_unused:UNUSED_PAD src0_sel:DWORD src1_sel:BYTE_0
	v_lshlrev_b32_e32 v2, 1, v1
	v_lshrrev_b32_e32 v3, 2, v1
	s_add_u32 s28, s56, s12
	v_bfe_i32 v16, v0, 0, 16
	v_and_b32_e32 v2, 24, v2
	v_and_b32_e32 v3, 4, v3
	s_addc_u32 s29, s57, s13
	s_add_i32 s50, s27, 0
	v_add_u32_e32 v0, v15, v16
	v_or3_b32 v2, v4, v3, v2
	v_mul_lo_u32 v1, v1, s1
	s_add_i32 m0, s50, 0x10000
	v_add_lshl_u32 v148, v0, v1, 1
	v_mul_u32_u24_e32 v1, 0x1600, v2
	global_load_lds_dwordx4 v146, s[28:29]
	s_add_i32 m0, s50, 0x12000
	v_add_lshl_u32 v150, v1, v0, 1
	s_add_u32 s12, s28, 0x160000
	global_load_lds_dwordx4 v150, s[28:29]
	s_addc_u32 s13, s29, 0
	s_add_i32 m0, s50, 0x14000
	s_mul_i32 s15, s92, 0x2c0000
	global_load_lds_dwordx4 v146, s[12:13]
	s_add_i32 m0, s50, 0x16000
	s_mul_hi_i32 s7, s92, 0x2c0000
	s_add_u32 s24, s46, s15
	s_addc_u32 s25, s47, s7
	s_add_i32 s51, s50, 0x2000
	global_load_lds_dwordx4 v150, s[12:13]
	s_mov_b32 m0, s50
	s_add_u32 s12, s24, 0x160000
	global_load_lds_dwordx4 v144, s[24:25]
	s_mov_b32 m0, s51
	s_addc_u32 s13, s25, 0
	s_add_i32 s71, s50, 0x4000
	global_load_lds_dwordx4 v148, s[24:25]
	s_mov_b32 m0, s71
	s_add_i32 s72, s50, 0x6000
	global_load_lds_dwordx4 v144, s[12:13]
	s_mov_b32 m0, s72
	v_mov_b32_e32 v147, 0
	global_load_lds_dwordx4 v148, s[12:13]
	v_mov_b32_e32 v151, v147
	v_mov_b32_e32 v145, v147
	v_mov_b32_e32 v149, v147
	s_cmp_eq_u32 s0, 1
	s_mov_b32 s73, 0
	v_lshl_add_u64 v[6:7], s[28:29], 0, v[146:147]
	v_lshl_add_u64 v[2:3], s[28:29], 0, v[150:151]
	s_mov_b32 s7, 0x16000
	v_lshl_add_u64 v[0:1], s[24:25], 0, v[144:145]
	s_cselect_b64 s[12:13], -1, 0
	s_cmp_lg_u32 s0, 1
	v_lshl_add_u64 v[4:5], s[24:25], 0, v[148:149]
	s_setprio 1
	s_cbranch_scc1 .LBB0_114
	s_barrier
	s_setprio 0

; #define PG8_STAGE(bufoff, gbase, voff) do { _Pragma("unroll") for (int _i = 0; _i < 2; ++_i) \
;         __builtin_amdgcn_global_load_lds((const unsigned*)((const char*)(gbase) + (voff)[_i]), (LAS unsigned*)(lds + (bufoff) + ldsw + _i * 8192), 16, 0, 0); } while (0)
; #define PG8_BAR __builtin_amdgcn_s_barrier()
; template <class Epi, bool ALIGN_EPI, class Hook = NoHook>
; __device__ __forceinline__ void gemm_phase(LAS unsigned char* lds, const Gemm g, const StaticOrder& S, const Epi& E, const Hook& HK = Hook()) {
;     int tid = threadIdx.x; asm volatile("" : "+v"(tid));
;     const int wid = __builtin_amdgcn_readfirstlane(tid >> 6), lane = tid & 63, wr = wid >> 2, wc = wid & 3, fr = lane & 15, fq = lane >> 4;
;     const int K = g.K, nt = K / BK;
;     unsigned voffA[2], voffB[2];
; #pragma unroll
;     for (int i = 0; i < 2; ++i) { int R, C; stage_rc(tid * 16 + i * 8192, R, C); const int Rb = Epi::PERM ? ((R & ~31) + perm32(R & 31)) : R;
;         voffA[i] = (unsigned)(R * g.lda + C) * 2u; voffB[i] = (unsigned)(Rb * g.ldb + C) * 2u; }
;     const size_t kstep = (size_t)(BK * 2);
;     const size_t hstepA = (size_t)HALF * g.lda * 2, hstepB = (size_t)HALF * g.ldb * 2;
;     const size_t tstepA = 2 * hstepA, tstepB = 2 * hstepB;
;     const unsigned ldsw = (unsigned)wid * 1024u;
;     const int aoff = lds_byte(wr * 64 + fr, fq * 8), boff = lds_byte(wc * 32 + fr, fq * 8);
;     ...
;     Unit cur, nxt; int ui = 0;
;     if (!S.next(0, cur)) return;
;     f32x4 acc[2][2][4][2];
; #pragma unroll
;     for (int a = 0; a < 2; ++a)
; #pragma unroll
;         for (int b = 0; b < 2; ++b)
; #pragma unroll
;             for (int m = 0; m < 4; ++m)
; #pragma unroll
;                 for (int n = 0; n < 2; ++n) acc[a][b][m][n] = (f32x4){0.f, 0.f, 0.f, 0.f};
;     bf16x8 At[4][2], B0[2][2], B1[2][2];
;     const char* cA = (const char*)g.A + (size_t)cur.pm * tstepA; const char* cB = (const char*)g.Bt + (size_t)cur.pn * tstepB;
;     PG8_STAGE(PG8_SB(0, 0), cB, voffB); PG8_STAGE(PG8_SB(0, 1), cB + hstepB, voffB); PG8_STAGE(PG8_SA(0, 0), cA, voffA); PG8_STAGE(PG8_SA(0, 1), cA + hstepA, voffA);
;     if (wr == 1) PG8_BAR;
.LBB0_261:
	s_add_u32 s76, s62, 0x17c00000
	s_addc_u32 s77, s63, 0
	s_andn2_b64 vcc, exec, s[0:1]
	s_cbranch_vccnz .LBB0_349
	v_ashrrev_i32_e32 v1, 31, v8
	v_lshrrev_b32_e32 v1, 26, v1
	v_add_u32_e32 v1, v8, v1
	v_ashrrev_i32_e32 v9, 6, v1
	v_bfe_i32 v1, v8, 27, 1
	v_lshlrev_b32_e32 v0, 4, v8
	v_lshrrev_b32_e32 v1, 22, v1
	v_add_u32_e32 v1, v0, v1
	v_and_b32_e32 v1, 0xfffffc00, v1
	v_sub_u32_e32 v1, v0, v1
	v_lshrrev_b32_e32 v2, 4, v1
	v_bitop3_b32 v1, v2, v1, 32 bitop3:0x6c
	v_ashrrev_i32_e32 v3, 31, v1
	v_lshrrev_b32_e32 v3, 26, v3
	v_add_u32_e32 v3, v1, v3
	v_lshlrev_b32_e32 v2, 3, v9
	v_ashrrev_i32_e32 v10, 6, v3
	v_and_b32_e32 v3, 0xc0, v3
	v_and_b32_e32 v2, -16, v2
	v_sub_u32_e32 v1, v1, v3
	v_mov_b32_e32 v3, 1
	v_add_u32_e32 v2, v10, v2
	v_ashrrev_i16_sdwa v1, v3, sext(v1) dst_sel:DWORD dst_unused:UNUSED_PAD src0_sel:DWORD src1_sel:BYTE_0
	v_lshlrev_b32_e32 v4, 5, v9
	v_bfe_i32 v11, v1, 0, 16
	v_lshlrev_b32_e32 v1, 1, v2
	v_lshrrev_b32_e32 v5, 2, v2
	v_and_b32_e32 v6, 3, v10
	s_mov_b32 s1, 0xfffe0
	v_and_b32_e32 v4, 32, v4
	v_and_b32_e32 v1, 24, v1
	v_and_b32_e32 v5, 4, v5
	v_and_or_b32 v6, v2, s1, v6
	v_or3_b32 v1, v6, v5, v1
	v_add_lshl_u32 v4, v4, v11, 1
	v_add_u32_e32 v0, 0x2000, v0
	v_lshl_add_u32 v134, v1, 12, v4
	v_ashrrev_i32_e32 v1, 31, v0
	v_lshrrev_b32_e32 v1, 22, v1
	v_add_u32_e32 v1, v0, v1
	v_ashrrev_i32_e32 v12, 10, v1
	v_mul_i32_i24_e32 v1, 0x400, v12
	v_sub_u32_e32 v0, v0, v1
	v_lshrrev_b32_e32 v1, 4, v0
	v_bitop3_b32 v0, v1, v0, 32 bitop3:0x6c
	v_lshl_add_u32 v130, v2, 12, v4
	v_ashrrev_i32_e32 v2, 31, v0
	v_lshrrev_b32_e32 v2, 26, v2
	v_add_u32_e32 v2, v0, v2
	v_lshlrev_b32_e32 v1, 3, v12
	v_ashrrev_i32_e32 v13, 6, v2
	v_and_b32_e32 v2, 0xc0, v2
	v_and_b32_e32 v1, -16, v1
	v_sub_u32_e32 v0, v0, v2
	v_add_u32_e32 v1, v13, v1
	v_ashrrev_i16_sdwa v0, v3, sext(v0) dst_sel:DWORD dst_unused:UNUSED_PAD src0_sel:DWORD src1_sel:BYTE_0
	v_and_b32_e32 v3, 3, v13
	v_and_or_b32 v3, v1, s1, v3
	s_ashr_i32 s1, s8, 6
	s_ashr_i32 s5, s4, 31
	s_ashr_i32 s85, s84, 31
	s_ashr_i32 s0, s8, 8
	s_lshl_b32 s17, s1, 10
	s_lshl_b64 s[6:7], s[4:5], 20
	s_lshl_b64 s[12:13], s[84:85], 20
	s_add_u32 s88, s80, s12
	v_lshlrev_b32_e32 v4, 5, v12
	v_bfe_i32 v14, v0, 0, 16
	v_lshlrev_b32_e32 v0, 1, v1
	v_lshrrev_b32_e32 v2, 2, v1
	s_addc_u32 s89, s81, s13
	s_add_i32 s28, s17, 0
	v_and_b32_e32 v4, 32, v4
	v_and_b32_e32 v0, 24, v0
	v_and_b32_e32 v2, 4, v2
	s_add_i32 m0, s28, 0x10000
	v_or3_b32 v0, v3, v2, v0
	v_add_lshl_u32 v2, v4, v14, 1
	global_load_lds_dwordx4 v134, s[88:89]
	s_add_i32 m0, s28, 0x12000
	v_lshl_add_u32 v146, v0, 12, v2
	s_add_u32 s12, s88, 0x80000
	global_load_lds_dwordx4 v146, s[88:89]
	s_addc_u32 s13, s89, 0
	s_add_i32 m0, s28, 0x14000
	v_lshl_add_u32 v144, v1, 12, v2
	global_load_lds_dwordx4 v134, s[12:13]
	s_add_i32 m0, s28, 0x16000
	s_add_u32 s86, s48, s6
	s_addc_u32 s87, s49, s7
	s_add_i32 s29, s28, 0x2000
	global_load_lds_dwordx4 v146, s[12:13]
	s_mov_b32 m0, s28
	s_add_u32 s6, s86, 0x80000
	global_load_lds_dwordx4 v130, s[86:87]
	s_mov_b32 m0, s29
	s_addc_u32 s7, s87, 0
	s_add_i32 s71, s28, 0x4000
	global_load_lds_dwordx4 v144, s[86:87]
	s_mov_b32 m0, s71
	s_add_i32 s82, s28, 0x6000
	global_load_lds_dwordx4 v130, s[6:7]
	s_mov_b32 m0, s82
	v_mov_b32_e32 v135, 0
	global_load_lds_dwordx4 v144, s[6:7]
	v_mov_b32_e32 v147, v135
	v_mov_b32_e32 v131, v135
	v_mov_b32_e32 v145, v135
	s_cmp_eq_u32 s0, 1
	s_mov_b64 s[54:55], s[56:57]
	s_mov_b64 s[56:57], s[34:35]
	s_mov_b32 s83, 0
	v_lshl_add_u64 v[6:7], s[88:89], 0, v[134:135]
	v_lshl_add_u64 v[4:5], s[88:89], 0, v[146:147]
	v_lshl_add_u64 v[0:1], s[86:87], 0, v[130:131]
	s_cselect_b64 s[6:7], -1, 0
	s_cmp_lg_u32 s0, 1
	v_lshl_add_u64 v[2:3], s[86:87], 0, v[144:145]
	s_setprio 1
	s_cbranch_scc1 .LBB0_264
	s_barrier
	s_setprio 0

; #define PG8_STAGE(bufoff, gbase, voff) do { _Pragma("unroll") for (int _i = 0; _i < 2; ++_i) \
;         __builtin_amdgcn_global_load_lds((const unsigned*)((const char*)(gbase) + (voff)[_i]), (LAS unsigned*)(lds + (bufoff) + ldsw + _i * 8192), 16, 0, 0); } while (0)
; #define PG8_BAR __builtin_amdgcn_s_barrier()
; template <class Epi, bool ALIGN_EPI, class Hook = NoHook>
; __device__ __forceinline__ void gemm_phase(LAS unsigned char* lds, const Gemm g, const StaticOrder& S, const Epi& E, const Hook& HK = Hook()) {
;     int tid = threadIdx.x; asm volatile("" : "+v"(tid));
;     const int wid = __builtin_amdgcn_readfirstlane(tid >> 6), lane = tid & 63, wr = wid >> 2, wc = wid & 3, fr = lane & 15, fq = lane >> 4;
;     const int K = g.K, nt = K / BK;
;     unsigned voffA[2], voffB[2];
; #pragma unroll
;     for (int i = 0; i < 2; ++i) { int R, C; stage_rc(tid * 16 + i * 8192, R, C); const int Rb = Epi::PERM ? ((R & ~31) + perm32(R & 31)) : R;
;         voffA[i] = (unsigned)(R * g.lda + C) * 2u; voffB[i] = (unsigned)(Rb * g.ldb + C) * 2u; }
;     const size_t kstep = (size_t)(BK * 2);
;     const size_t hstepA = (size_t)HALF * g.lda * 2, hstepB = (size_t)HALF * g.ldb * 2;
;     const size_t tstepA = 2 * hstepA, tstepB = 2 * hstepB;
;     const unsigned ldsw = (unsigned)wid * 1024u;
;     const int aoff = lds_byte(wr * 64 + fr, fq * 8), boff = lds_byte(wc * 32 + fr, fq * 8);
;     ...
;     Unit cur, nxt; int ui = 0;
;     if (!S.next(0, cur)) return;
;     f32x4 acc[2][2][4][2];
; #pragma unroll
;     for (int a = 0; a < 2; ++a)
; #pragma unroll
;         for (int b = 0; b < 2; ++b)
; #pragma unroll
;             for (int m = 0; m < 4; ++m)
; #pragma unroll
;                 for (int n = 0; n < 2; ++n) acc[a][b][m][n] = (f32x4){0.f, 0.f, 0.f, 0.f};
;     bf16x8 At[4][2], B0[2][2], B1[2][2];
;     const char* cA = (const char*)g.A + (size_t)cur.pm * tstepA; const char* cB = (const char*)g.Bt + (size_t)cur.pn * tstepB;
;     PG8_STAGE(PG8_SB(0, 0), cB, voffB); PG8_STAGE(PG8_SB(0, 1), cB + hstepB, voffB); PG8_STAGE(PG8_SA(0, 0), cA, voffA); PG8_STAGE(PG8_SA(0, 1), cA + hstepA, voffA);
;     if (wr == 1) PG8_BAR;
.LBB0_775:
	v_ashrrev_i32_e32 v1, 31, v8
	v_lshrrev_b32_e32 v1, 26, v1
	v_add_u32_e32 v1, v8, v1
	v_ashrrev_i32_e32 v9, 6, v1
	v_bfe_i32 v1, v8, 27, 1
	v_lshlrev_b32_e32 v0, 4, v8
	v_lshrrev_b32_e32 v1, 22, v1
	v_add_u32_e32 v1, v0, v1
	v_and_b32_e32 v1, 0xfffffc00, v1
	v_sub_u32_e32 v1, v0, v1
	v_lshrrev_b32_e32 v2, 4, v1
	v_bitop3_b32 v1, v2, v1, 32 bitop3:0x6c
	v_ashrrev_i32_e32 v3, 31, v1
	v_lshrrev_b32_e32 v3, 26, v3
	v_add_u32_e32 v3, v1, v3
	v_lshlrev_b32_e32 v2, 3, v9
	v_ashrrev_i32_e32 v10, 6, v3
	v_and_b32_e32 v3, 0xc0, v3
	v_and_b32_e32 v2, -16, v2
	v_sub_u32_e32 v1, v1, v3
	v_mov_b32_e32 v3, 1
	v_add_u32_e32 v2, v10, v2
	v_ashrrev_i16_sdwa v1, v3, sext(v1) dst_sel:DWORD dst_unused:UNUSED_PAD src0_sel:DWORD src1_sel:BYTE_0
	s_ashr_i32 s0, s7, 3
	v_lshlrev_b32_e32 v4, 5, v9
	v_bfe_i32 v11, v1, 0, 16
	v_lshlrev_b32_e32 v1, 1, v2
	v_lshrrev_b32_e32 v5, 2, v2
	v_and_b32_e32 v6, 3, v10
	s_mov_b32 s7, 0xfffe0
	v_and_b32_e32 v4, 32, v4
	v_and_b32_e32 v1, 24, v1
	v_and_b32_e32 v5, 4, v5
	v_and_or_b32 v6, v2, s7, v6
	v_or3_b32 v1, v6, v5, v1
	v_add_lshl_u32 v4, v4, v11, 1
	v_add_u32_e32 v0, 0x2000, v0
	v_lshl_add_u32 v130, v1, 12, v4
	v_ashrrev_i32_e32 v1, 31, v0
	v_lshrrev_b32_e32 v1, 22, v1
	v_add_u32_e32 v1, v0, v1
	v_ashrrev_i32_e32 v12, 10, v1
	v_mul_i32_i24_e32 v1, 0x400, v12
	v_sub_u32_e32 v0, v0, v1
	v_lshrrev_b32_e32 v1, 4, v0
	v_bitop3_b32 v0, v1, v0, 32 bitop3:0x6c
	v_lshl_add_u32 v128, v2, 12, v4
	v_ashrrev_i32_e32 v2, 31, v0
	v_lshrrev_b32_e32 v2, 26, v2
	v_add_u32_e32 v2, v0, v2
	s_add_i32 s0, s6, s0
	v_lshlrev_b32_e32 v1, 3, v12
	v_ashrrev_i32_e32 v13, 6, v2
	v_and_b32_e32 v2, 0xc0, v2
	s_ashr_i32 s6, s0, 31
	v_and_b32_e32 v1, -16, v1
	v_sub_u32_e32 v0, v0, v2
	s_lshr_b32 s6, s6, 27
	v_add_u32_e32 v1, v13, v1
	v_ashrrev_i16_sdwa v0, v3, sext(v0) dst_sel:DWORD dst_unused:UNUSED_PAD src0_sel:DWORD src1_sel:BYTE_0
	v_and_b32_e32 v3, 3, v13
	s_add_i32 s6, s0, s6
	v_and_or_b32 v3, v1, s7, v3
	s_ashr_i32 s7, s6, 5
	s_andn2_b32 s6, s6, 31
	s_sub_i32 s6, s0, s6
	s_bfe_i32 s0, s6, 0x80000
	s_bfe_u32 s0, s0, 0x2000d
	s_add_i32 s8, s6, s0
	s_bfe_i32 s0, s8, 0x80000
	s_and_b32 s8, s8, 0xfc
	s_sub_i32 s6, s6, s8
	s_lshl_b32 s7, s7, 2
	s_sext_i32_i16 s0, s0
	s_sext_i32_i8 s6, s6
	s_ashr_i32 s1, s12, 8
	s_lshr_b32 s0, s0, 2
	s_add_i32 s38, s7, s6
	s_ashr_i32 s10, s12, 6
	s_ashr_i32 s39, s38, 31
	s_bfe_i64 s[8:9], s[0:1], 0x100000
	s_lshl_b32 s27, s10, 10
	s_lshl_b64 s[6:7], s[38:39], 20
	s_lshl_b64 s[8:9], s[8:9], 20
	s_add_u32 s42, s74, s8
	v_lshlrev_b32_e32 v4, 5, v12
	v_bfe_i32 v14, v0, 0, 16
	v_lshlrev_b32_e32 v0, 1, v1
	v_lshrrev_b32_e32 v2, 2, v1
	s_addc_u32 s43, s75, s9
	s_add_i32 s28, s27, 0
	v_and_b32_e32 v4, 32, v4
	v_and_b32_e32 v0, 24, v0
	v_and_b32_e32 v2, 4, v2
	s_add_i32 m0, s28, 0x10000
	v_or3_b32 v0, v3, v2, v0
	v_add_lshl_u32 v2, v4, v14, 1
	global_load_lds_dwordx4 v130, s[42:43]
	s_add_i32 m0, s28, 0x12000
	v_lshl_add_u32 v134, v0, 12, v2
	s_add_u32 s8, s42, 0x80000
	global_load_lds_dwordx4 v134, s[42:43]
	s_addc_u32 s9, s43, 0
	s_add_i32 m0, s28, 0x14000
	v_lshl_add_u32 v132, v1, 12, v2
	global_load_lds_dwordx4 v130, s[8:9]
	s_add_i32 m0, s28, 0x16000
	s_add_u32 s40, s66, s6
	s_addc_u32 s41, s67, s7
	s_add_i32 s29, s28, 0x2000
	global_load_lds_dwordx4 v134, s[8:9]
	s_mov_b32 m0, s28
	s_add_u32 s6, s40, 0x80000
	global_load_lds_dwordx4 v128, s[40:41]
	s_mov_b32 m0, s29
	s_addc_u32 s7, s41, 0
	s_add_i32 s39, s28, 0x4000
	global_load_lds_dwordx4 v132, s[40:41]
	s_mov_b32 m0, s39
	s_add_i32 s50, s28, 0x6000
	global_load_lds_dwordx4 v128, s[6:7]
	s_mov_b32 m0, s50
	v_mov_b32_e32 v131, 0
	global_load_lds_dwordx4 v132, s[6:7]
	v_mov_b32_e32 v135, v131
	v_mov_b32_e32 v129, v131
	v_mov_b32_e32 v133, v131
	s_cmp_eq_u32 s1, 1
	s_mov_b32 s51, 0
	v_lshl_add_u64 v[6:7], s[42:43], 0, v[130:131]
	v_lshl_add_u64 v[2:3], s[42:43], 0, v[134:135]
	s_mov_b64 s[6:7], 0x80000
	v_lshl_add_u64 v[0:1], s[40:41], 0, v[128:129]
	s_cselect_b64 s[8:9], -1, 0
	s_cmp_lg_u32 s1, 1
	v_lshl_add_u64 v[4:5], s[40:41], 0, v[132:133]
	s_setprio 1
	s_cbranch_scc1 .LBB0_777
	s_barrier
	s_setprio 0

; #define PG8_STAGE(bufoff, gbase, voff) do { _Pragma("unroll") for (int _i = 0; _i < 2; ++_i) \
;         __builtin_amdgcn_global_load_lds((const unsigned*)((const char*)(gbase) + (voff)[_i]), (LAS unsigned*)(lds + (bufoff) + ldsw + _i * 8192), 16, 0, 0); } while (0)
; #define PG8_BAR __builtin_amdgcn_s_barrier()
; template <class Epi, bool ALIGN_EPI, class Hook = NoHook>
; __device__ __forceinline__ void gemm_phase(LAS unsigned char* lds, const Gemm g, const StaticOrder& S, const Epi& E, const Hook& HK = Hook()) {
;     int tid = threadIdx.x; asm volatile("" : "+v"(tid));
;     const int wid = __builtin_amdgcn_readfirstlane(tid >> 6), lane = tid & 63, wr = wid >> 2, wc = wid & 3, fr = lane & 15, fq = lane >> 4;
;     const int K = g.K, nt = K / BK;
;     unsigned voffA[2], voffB[2];
; #pragma unroll
;     for (int i = 0; i < 2; ++i) { int R, C; stage_rc(tid * 16 + i * 8192, R, C); const int Rb = Epi::PERM ? ((R & ~31) + perm32(R & 31)) : R;
;         voffA[i] = (unsigned)(R * g.lda + C) * 2u; voffB[i] = (unsigned)(Rb * g.ldb + C) * 2u; }
;     const size_t kstep = (size_t)(BK * 2);
;     const size_t hstepA = (size_t)HALF * g.lda * 2, hstepB = (size_t)HALF * g.ldb * 2;
;     const size_t tstepA = 2 * hstepA, tstepB = 2 * hstepB;
;     const unsigned ldsw = (unsigned)wid * 1024u;
;     const int aoff = lds_byte(wr * 64 + fr, fq * 8), boff = lds_byte(wc * 32 + fr, fq * 8);
;     ...
;     Unit cur, nxt; int ui = 0;
;     if (!S.next(0, cur)) return;
;     f32x4 acc[2][2][4][2];
; #pragma unroll
;     for (int a = 0; a < 2; ++a)
; #pragma unroll
;         for (int b = 0; b < 2; ++b)
; #pragma unroll
;             for (int m = 0; m < 4; ++m)
; #pragma unroll
;                 for (int n = 0; n < 2; ++n) acc[a][b][m][n] = (f32x4){0.f, 0.f, 0.f, 0.f};
;     bf16x8 At[4][2], B0[2][2], B1[2][2];
;     const char* cA = (const char*)g.A + (size_t)cur.pm * tstepA; const char* cB = (const char*)g.Bt + (size_t)cur.pn * tstepB;
;     PG8_STAGE(PG8_SB(0, 0), cB, voffB); PG8_STAGE(PG8_SB(0, 1), cB + hstepB, voffB); PG8_STAGE(PG8_SA(0, 0), cA, voffA); PG8_STAGE(PG8_SA(0, 1), cA + hstepA, voffA);
;     if (wr == 1) PG8_BAR;
.LBB0_910:
	s_or_b64 exec, exec, s[0:1]
	v_readlane_b32 s0, v254, 16
	v_mov_b32_e32 v9, v136
	v_readlane_b32 s1, v254, 17
	s_waitcnt lgkmcnt(0)
	s_barrier
	s_andn2_b64 vcc, exec, s[0:1]
	v_readfirstlane_b32 s1, v9
	s_cbranch_vccnz .LBB0_926
	v_lshlrev_b32_e32 v0, 4, v9
	v_add_u32_e32 v1, 0x2000, v0
	v_ashrrev_i32_e32 v2, 31, v1
	v_lshrrev_b32_e32 v2, 22, v2
	v_add_u32_e32 v2, v1, v2
	v_ashrrev_i32_e32 v8, 10, v2
	v_mul_i32_i24_e32 v2, 0x400, v8
	v_sub_u32_e32 v1, v1, v2
	v_lshrrev_b32_e32 v2, 4, v1
	v_bitop3_b32 v1, v2, v1, 32 bitop3:0x6c
	v_ashrrev_i32_e32 v2, 31, v1
	v_lshrrev_b32_e32 v2, 26, v2
	v_add_u32_e32 v2, v1, v2
	v_lshlrev_b32_e32 v3, 3, v8
	v_ashrrev_i32_e32 v10, 6, v2
	v_and_b32_e32 v3, -16, v3
	v_add_u32_e32 v3, v10, v3
	v_and_b32_e32 v4, 3, v10
	s_mov_b32 s0, 0xfffe0
	v_lshrrev_b32_e32 v5, 2, v3
	v_lshlrev_b32_e32 v6, 1, v3
	v_and_b32_e32 v2, 0xc0, v2
	v_and_or_b32 v4, v3, s0, v4
	v_and_b32_e32 v5, 4, v5
	v_and_b32_e32 v6, 24, v6
	v_sub_u32_e32 v1, v1, v2
	v_mov_b32_e32 v2, 1
	v_or3_b32 v4, v4, v5, v6
	v_lshlrev_b32_e32 v5, 5, v8
	v_ashrrev_i16_sdwa v1, v2, sext(v1) dst_sel:DWORD dst_unused:UNUSED_PAD src0_sel:DWORD src1_sel:BYTE_0
	v_and_b32_e32 v5, 32, v5
	v_bfe_i32 v11, v1, 0, 16
	v_add_lshl_u32 v1, v5, v11, 1
	v_lshl_add_u32 v128, v4, 12, v1
	v_lshl_add_u32 v130, v3, 12, v1
	v_bfe_i32 v1, v9, 27, 1
	v_lshrrev_b32_e32 v1, 22, v1
	v_add_u32_e32 v1, v0, v1
	v_and_b32_e32 v1, 0xfffffc00, v1
	v_sub_u32_e32 v0, v0, v1
	v_lshrrev_b32_e32 v1, 4, v0
	v_ashrrev_i32_e32 v3, 31, v9
	v_bitop3_b32 v0, v1, v0, 32 bitop3:0x6c
	v_lshrrev_b32_e32 v3, 26, v3
	v_ashrrev_i32_e32 v1, 31, v0
	v_add_u32_e32 v3, v9, v3
	v_lshrrev_b32_e32 v1, 26, v1
	v_ashrrev_i32_e32 v13, 6, v3
	v_add_u32_e32 v1, v0, v1
	v_lshlrev_b32_e32 v3, 3, v13
	v_ashrrev_i32_e32 v12, 6, v1
	v_and_b32_e32 v3, -16, v3
	v_add_u32_e32 v3, v12, v3
	v_and_b32_e32 v4, 3, v12
	s_ashr_i32 s26, s2, 31
	v_and_or_b32 v4, v3, s0, v4
	s_lshr_b32 s0, s26, 29
	s_add_i32 s0, s2, s0
	s_ashr_i32 s8, s1, 6
	s_ashr_i32 s6, s0, 3
	s_and_b32 s0, s0, -8
	s_ashr_i32 s10, s1, 8
	s_lshl_b32 s13, s8, 10
	s_sub_i32 s0, s2, s0
	s_cmp_lt_i32 s0, 0
	s_movk_i32 s27, 0x161
	s_cselect_b32 s7, s27, 0x160
	s_mul_i32 s0, s0, s7
	s_add_i32 s0, s0, s6
	s_mul_hi_i32 s6, s0, 0x2e8ba2e9
	s_lshr_b32 s7, s6, 31
	s_ashr_i32 s6, s6, 6
	s_add_i32 s6, s6, s7
	s_lshl_b32 s7, s6, 3
	s_mulk_i32 s6, 0x160
	s_sub_i32 s6, s0, s6
	s_sext_i32_i16 s0, s6
	s_bfe_u32 s0, s0, 0x3001c
	s_add_i32 s9, s6, s0
	s_sext_i32_i16 s0, s9
	s_and_b32 s9, s9, 0xfff8
	s_sub_i32 s6, s6, s9
	s_sext_i32_i16 s6, s6
	v_lshrrev_b32_e32 v5, 2, v3
	v_lshlrev_b32_e32 v6, 1, v3
	v_and_b32_e32 v1, 0xc0, v1
	s_lshr_b32 s0, s0, 3
	s_add_i32 s22, s7, s6
	v_and_b32_e32 v5, 4, v5
	v_and_b32_e32 v6, 24, v6
	v_sub_u32_e32 v0, v0, v1
	s_ashr_i32 s23, s22, 31
	s_bfe_i64 s[14:15], s[0:1], 0x100000
	v_or3_b32 v4, v4, v5, v6
	v_lshlrev_b32_e32 v5, 5, v13
	v_ashrrev_i16_sdwa v0, v2, sext(v0) dst_sel:DWORD dst_unused:UNUSED_PAD src0_sel:DWORD src1_sel:BYTE_0
	s_lshl_b64 s[6:7], s[22:23], 20
	s_lshl_b64 s[14:15], s[14:15], 20
	v_and_b32_e32 v5, 32, v5
	v_bfe_i32 v14, v0, 0, 16
	s_add_u32 s28, s66, s14
	v_add_lshl_u32 v0, v5, v14, 1
	s_addc_u32 s29, s67, s15
	s_add_i32 s23, s13, 0
	v_lshl_add_u32 v132, v4, 12, v0
	s_add_i32 m0, s23, 0x10000
	v_lshl_add_u32 v134, v3, 12, v0
	global_load_lds_dwordx4 v132, s[28:29]
	s_add_i32 m0, s23, 0x12000
	s_add_u32 s14, s28, 0x80000
	global_load_lds_dwordx4 v128, s[28:29]
	s_addc_u32 s15, s29, 0
	s_add_i32 m0, s23, 0x14000
	v_mov_b32_e32 v133, 0
	global_load_lds_dwordx4 v132, s[14:15]
	s_add_i32 m0, s23, 0x16000
	s_add_u32 s24, s48, s6
	s_addc_u32 s25, s49, s7
	s_add_i32 s33, s23, 0x2000
	global_load_lds_dwordx4 v128, s[14:15]
	s_mov_b32 m0, s23
	s_add_u32 s6, s24, 0x80000
	global_load_lds_dwordx4 v134, s[24:25]
	s_mov_b32 m0, s33
	s_addc_u32 s7, s25, 0
	s_add_i32 s38, s23, 0x4000
	global_load_lds_dwordx4 v130, s[24:25]
	s_mov_b32 m0, s38
	s_add_i32 s39, s23, 0x6000
	global_load_lds_dwordx4 v134, s[6:7]
	s_mov_b32 m0, s39
	v_mov_b32_e32 v129, v133
	global_load_lds_dwordx4 v130, s[6:7]
	v_mov_b32_e32 v135, v133
	v_mov_b32_e32 v131, v133
	s_cmp_eq_u32 s10, 1
	s_mov_b32 s40, 0
	v_lshl_add_u64 v[6:7], s[28:29], 0, v[132:133]
	v_lshl_add_u64 v[4:5], s[28:29], 0, v[128:129]
	v_lshl_add_u64 v[0:1], s[24:25], 0, v[134:135]
	s_cselect_b64 s[6:7], -1, 0
	s_cmp_lg_u32 s10, 1
	v_lshl_add_u64 v[2:3], s[24:25], 0, v[130:131]
	s_setprio 1
	s_cbranch_scc1 .LBB0_913
	s_barrier
	s_setprio 0

; #define PG8_STAGE(bufoff, gbase, voff) do { _Pragma("unroll") for (int _i = 0; _i < 2; ++_i) \
;         __builtin_amdgcn_global_load_lds((const unsigned*)((const char*)(gbase) + (voff)[_i]), (LAS unsigned*)(lds + (bufoff) + ldsw + _i * 8192), 16, 0, 0); } while (0)
; #define PG8_BAR __builtin_amdgcn_s_barrier()
; template <class Epi, bool ALIGN_EPI, class Hook = NoHook>
; __device__ __forceinline__ void gemm_phase(LAS unsigned char* lds, const Gemm g, const StaticOrder& S, const Epi& E, const Hook& HK = Hook()) {
;     int tid = threadIdx.x; asm volatile("" : "+v"(tid));
;     const int wid = __builtin_amdgcn_readfirstlane(tid >> 6), lane = tid & 63, wr = wid >> 2, wc = wid & 3, fr = lane & 15, fq = lane >> 4;
;     const int K = g.K, nt = K / BK;
;     unsigned voffA[2], voffB[2];
; #pragma unroll
;     for (int i = 0; i < 2; ++i) { int R, C; stage_rc(tid * 16 + i * 8192, R, C); const int Rb = Epi::PERM ? ((R & ~31) + perm32(R & 31)) : R;
;         voffA[i] = (unsigned)(R * g.lda + C) * 2u; voffB[i] = (unsigned)(Rb * g.ldb + C) * 2u; }
;     const size_t kstep = (size_t)(BK * 2);
;     const size_t hstepA = (size_t)HALF * g.lda * 2, hstepB = (size_t)HALF * g.ldb * 2;
;     const size_t tstepA = 2 * hstepA, tstepB = 2 * hstepB;
;     const unsigned ldsw = (unsigned)wid * 1024u;
;     const int aoff = lds_byte(wr * 64 + fr, fq * 8), boff = lds_byte(wc * 32 + fr, fq * 8);
;     ...
;     Unit cur, nxt; int ui = 0;
;     if (!S.next(0, cur)) return;
;     f32x4 acc[2][2][4][2];
; #pragma unroll
;     for (int a = 0; a < 2; ++a)
; #pragma unroll
;         for (int b = 0; b < 2; ++b)
; #pragma unroll
;             for (int m = 0; m < 4; ++m)
; #pragma unroll
;                 for (int n = 0; n < 2; ++n) acc[a][b][m][n] = (f32x4){0.f, 0.f, 0.f, 0.f};
;     bf16x8 At[4][2], B0[2][2], B1[2][2];
;     const char* cA = (const char*)g.A + (size_t)cur.pm * tstepA; const char* cB = (const char*)g.Bt + (size_t)cur.pn * tstepB;
;     PG8_STAGE(PG8_SB(0, 0), cB, voffB); PG8_STAGE(PG8_SB(0, 1), cB + hstepB, voffB); PG8_STAGE(PG8_SA(0, 0), cA, voffA); PG8_STAGE(PG8_SA(0, 1), cA + hstepA, voffA);
;     if (wr == 1) PG8_BAR;
.LBB0_983:
	v_ashrrev_i32_e32 v1, 31, v136
	v_lshrrev_b32_e32 v1, 26, v1
	v_add_u32_e32 v1, v136, v1
	v_ashrrev_i32_e32 v8, 6, v1
	v_bfe_i32 v1, v136, 27, 1
	v_lshlrev_b32_e32 v0, 4, v136
	v_lshrrev_b32_e32 v1, 22, v1
	v_add_u32_e32 v1, v0, v1
	v_and_b32_e32 v1, 0xfffffc00, v1
	v_sub_u32_e32 v1, v0, v1
	v_lshrrev_b32_e32 v2, 4, v1
	v_bitop3_b32 v1, v2, v1, 32 bitop3:0x6c
	v_ashrrev_i32_e32 v3, 31, v1
	v_lshrrev_b32_e32 v3, 26, v3
	v_lshlrev_b32_e32 v2, 3, v8
	v_add_u32_e32 v3, v1, v3
	v_and_b32_e32 v2, -16, v2
	v_ashrrev_i32_e32 v9, 6, v3
	v_and_b32_e32 v3, 0xc0, v3
	v_add_u32_e32 v2, v9, v2
	v_lshlrev_b32_e32 v4, 5, v8
	v_sub_u32_e32 v1, v1, v3
	v_mov_b32_e32 v3, 1
	v_and_b32_e32 v10, 32, v4
	v_ashrrev_i16_sdwa v1, v3, sext(v1) dst_sel:DWORD dst_unused:UNUSED_PAD src0_sel:DWORD src1_sel:BYTE_0
	v_lshlrev_b32_e32 v4, 1, v2
	v_lshrrev_b32_e32 v5, 2, v2
	v_and_b32_e32 v6, 3, v9
	s_mov_b32 s7, 0x7fffe0
	v_bfe_i32 v11, v1, 0, 16
	v_and_b32_e32 v4, 24, v4
	v_and_b32_e32 v5, 4, v5
	v_and_or_b32 v6, v2, s7, v6
	s_movk_i32 s1, 0x1600
	v_add_u32_e32 v1, v10, v11
	v_or3_b32 v4, v6, v5, v4
	v_mul_lo_u32 v2, v2, s1
	v_add_lshl_u32 v128, v1, v2, 1
	v_mul_u32_u24_e32 v2, 0x1600, v4
	v_add_u32_e32 v0, 0x2000, v0
	v_add_lshl_u32 v130, v2, v1, 1
	v_ashrrev_i32_e32 v1, 31, v0
	v_lshrrev_b32_e32 v1, 22, v1
	v_add_u32_e32 v1, v0, v1
	v_ashrrev_i32_e32 v12, 10, v1
	v_mul_i32_i24_e32 v1, 0x400, v12
	v_sub_u32_e32 v0, v0, v1
	v_lshrrev_b32_e32 v1, 4, v0
	v_bitop3_b32 v0, v1, v0, 32 bitop3:0x6c
	v_ashrrev_i32_e32 v2, 31, v0
	v_lshrrev_b32_e32 v2, 26, v2
	s_add_i32 s5, s5, s6
	v_lshlrev_b32_e32 v1, 3, v12
	v_add_u32_e32 v2, v0, v2
	s_ashr_i32 s6, s5, 31
	v_and_b32_e32 v1, -16, v1
	v_ashrrev_i32_e32 v13, 6, v2
	v_lshlrev_b32_e32 v4, 5, v12
	s_lshr_b32 s6, s6, 27
	v_add_u32_e32 v1, v13, v1
	v_and_b32_e32 v14, 32, v4
	v_and_b32_e32 v4, 3, v13
	s_add_i32 s6, s5, s6
	v_and_or_b32 v4, v1, s7, v4
	s_ashr_i32 s7, s6, 5
	s_and_b32 s6, s6, 0xffe0
	s_sub_i32 s6, s5, s6
	s_bfe_i32 s5, s6, 0x80000
	s_bfe_u32 s5, s5, 0x2000d
	s_add_i32 s9, s6, s5
	s_bfe_i32 s5, s9, 0x80000
	s_and_b32 s9, s9, 0xfc
	s_sub_i32 s6, s6, s9
	s_lshl_b32 s7, s7, 2
	s_sext_i32_i16 s10, s5
	s_sext_i32_i8 s6, s6
	v_and_b32_e32 v2, 0xc0, v2
	s_ashr_i32 s8, s4, 6
	s_add_i32 s39, s7, s6
	s_ashr_i32 s6, s10, 2
	s_ashr_i32 s0, s4, 8
	v_sub_u32_e32 v0, v0, v2
	s_lshl_b32 s22, s8, 10
	s_lshr_b32 s5, s10, 2
	s_mul_hi_i32 s7, s6, 0x2c0000
	s_mul_i32 s6, s6, 0x2c0000
	v_ashrrev_i16_sdwa v0, v3, sext(v0) dst_sel:DWORD dst_unused:UNUSED_PAD src0_sel:DWORD src1_sel:BYTE_0
	v_lshlrev_b32_e32 v2, 1, v1
	v_lshrrev_b32_e32 v3, 2, v1
	s_add_u32 s16, s88, s6
	v_bfe_i32 v15, v0, 0, 16
	v_and_b32_e32 v2, 24, v2
	v_and_b32_e32 v3, 4, v3
	s_addc_u32 s17, s89, s7
	s_add_i32 s23, s22, 0
	v_add_u32_e32 v0, v14, v15
	v_or3_b32 v2, v4, v3, v2
	v_mul_lo_u32 v1, v1, s1
	s_add_i32 m0, s23, 0x10000
	v_add_lshl_u32 v132, v0, v1, 1
	v_mul_u32_u24_e32 v1, 0x1600, v2
	global_load_lds_dwordx4 v130, s[16:17]
	s_add_i32 m0, s23, 0x12000
	v_add_lshl_u32 v134, v1, v0, 1
	s_add_u32 s6, s16, 0x160000
	global_load_lds_dwordx4 v134, s[16:17]
	s_addc_u32 s7, s17, 0
	s_add_i32 m0, s23, 0x14000
	s_mul_i32 s11, s39, 0x2c0000
	global_load_lds_dwordx4 v130, s[6:7]
	s_add_i32 m0, s23, 0x16000
	s_mul_hi_i32 s9, s39, 0x2c0000
	s_add_u32 s14, s46, s11
	s_addc_u32 s15, s47, s9
	s_add_i32 s24, s23, 0x2000
	global_load_lds_dwordx4 v134, s[6:7]
	s_mov_b32 m0, s23
	s_add_u32 s6, s14, 0x160000
	global_load_lds_dwordx4 v128, s[14:15]
	s_mov_b32 m0, s24
	s_addc_u32 s7, s15, 0
	s_add_i32 s25, s23, 0x4000
	global_load_lds_dwordx4 v132, s[14:15]
	s_mov_b32 m0, s25
	s_add_i32 s26, s23, 0x6000
	global_load_lds_dwordx4 v128, s[6:7]
	s_mov_b32 m0, s26
	v_mov_b32_e32 v131, 0
	global_load_lds_dwordx4 v132, s[6:7]
	v_mov_b32_e32 v135, v131
	v_mov_b32_e32 v129, v131
	v_mov_b32_e32 v133, v131
	s_cmp_eq_u32 s0, 1
	s_mov_b32 s27, 0
	v_lshl_add_u64 v[6:7], s[16:17], 0, v[130:131]
	v_lshl_add_u64 v[2:3], s[16:17], 0, v[134:135]
	s_mov_b32 s12, 0x16000
	v_lshl_add_u64 v[0:1], s[14:15], 0, v[128:129]
	s_cselect_b64 s[6:7], -1, 0
	s_cmp_lg_u32 s0, 1
	v_lshl_add_u64 v[4:5], s[14:15], 0, v[132:133]
	s_setprio 1
	s_cbranch_scc1 .LBB0_985
	s_barrier
	s_setprio 0
